# P0 x->fp8 copy with four 64-byte pieces per thread in flight, on top of lean sweep + LN2 preload + P6 epilogue + attention wait fix
# baseline (speedup 1.0000x reference)
.LBB0_35:
	s_ashr_i32 s91, s90, 31
	s_lshl_b64 s[12:13], s[90:91], 9
	s_ashr_i32 s19, s18, 31
	v_or_b32_e32 v2, s12, v0
	v_mov_b32_e32 v3, s13
	s_mov_b64 s[10:11], 0x200000
	s_lshl_b64 s[8:9], s[18:19], 9
	v_mov_b32_e32 v1, 0
	v_cmp_gt_u64_e32 vcc, s[10:11], v[2:3]
	s_and_saveexec_b64 s[10:11], vcc
	s_cbranch_execz .LBB0_38
	s_lshl_b64 s[14:15], s[90:91], 13
	s_add_u32 s14, s72, s14
	v_lshlrev_b32_e32 v4, 4, v0
	v_mov_b32_e32 v5, v1
	s_addc_u32 s15, s73, s15
	v_lshl_add_u64 v[4:5], s[14:15], 0, v[4:5]
	s_mov_b64 s[14:15], 0x19300000
	v_lshl_add_u64 v[4:5], v[4:5], 0, s[14:15]
	s_lshl_b64 s[14:15], s[18:19], 13
	s_lshl_b64 s[16:17], s[90:91], 15
	s_add_u32 s6, s6, s16
	v_lshlrev_b32_e32 v6, 6, v0
	v_mov_b32_e32 v7, v1
	s_addc_u32 s7, s7, s17
	v_lshl_add_u64 v[6:7], s[6:7], 0, v[6:7]
	s_lshl_b64 s[6:7], s[18:19], 15
	s_mov_b64 s[16:17], 0
	s_mov_b32 s20, 0x42000000
	s_mov_b32 s3, 0xc3e00000
	v_mov_b32_e32 v10, 0x43e00000
	s_mov_b64 s[22:23], 0x1fffff
	v_mov_b64_e32 v[8:9], v[2:3]
	s_cmpk_lg_i32 s18, 0x100
	s_cbranch_scc1 .LBB0_37
	global_load_dwordx4 v[80:83], v[6:7], off
	global_load_dwordx4 v[84:87], v[6:7], off offset:16
	global_load_dwordx4 v[88:91], v[6:7], off offset:32
	global_load_dwordx4 v[92:95], v[6:7], off offset:48
	v_lshl_add_u64 v[6:7], v[6:7], 0, s[6:7]
	global_load_dwordx4 v[96:99], v[6:7], off
	global_load_dwordx4 v[100:103], v[6:7], off offset:16
	global_load_dwordx4 v[104:107], v[6:7], off offset:32
	global_load_dwordx4 v[108:111], v[6:7], off offset:48
	v_lshl_add_u64 v[6:7], v[6:7], 0, s[6:7]
	global_load_dwordx4 v[112:115], v[6:7], off
	global_load_dwordx4 v[116:119], v[6:7], off offset:16
	global_load_dwordx4 v[120:123], v[6:7], off offset:32
	global_load_dwordx4 v[124:127], v[6:7], off offset:48
	v_lshl_add_u64 v[6:7], v[6:7], 0, s[6:7]
	global_load_dwordx4 v[128:131], v[6:7], off
	global_load_dwordx4 v[132:135], v[6:7], off offset:16
	global_load_dwordx4 v[136:139], v[6:7], off offset:32
	global_load_dwordx4 v[140:143], v[6:7], off offset:48
	v_lshl_add_u64 v[6:7], v[6:7], 0, s[6:7]
	s_waitcnt vmcnt(12)
	v_pk_mul_f32 v[80:81], v[80:81], s[20:21] op_sel_hi:[1,0]
	v_pk_mul_f32 v[82:83], v[82:83], s[20:21] op_sel_hi:[1,0]
	v_pk_mul_f32 v[84:85], v[84:85], s[20:21] op_sel_hi:[1,0]
	v_pk_mul_f32 v[86:87], v[86:87], s[20:21] op_sel_hi:[1,0]
	v_pk_mul_f32 v[88:89], v[88:89], s[20:21] op_sel_hi:[1,0]
	v_pk_mul_f32 v[90:91], v[90:91], s[20:21] op_sel_hi:[1,0]
	v_pk_mul_f32 v[92:93], v[92:93], s[20:21] op_sel_hi:[1,0]
	v_pk_mul_f32 v[94:95], v[94:95], s[20:21] op_sel_hi:[1,0]
	v_med3_f32 v80, v80, s3, v10
	v_med3_f32 v81, v81, s3, v10
	v_med3_f32 v82, v82, s3, v10
	v_med3_f32 v83, v83, s3, v10
	v_med3_f32 v84, v84, s3, v10
	v_med3_f32 v85, v85, s3, v10
	v_med3_f32 v86, v86, s3, v10
	v_med3_f32 v87, v87, s3, v10
	v_med3_f32 v88, v88, s3, v10
	v_med3_f32 v89, v89, s3, v10
	v_med3_f32 v90, v90, s3, v10
	v_med3_f32 v91, v91, s3, v10
	v_med3_f32 v92, v92, s3, v10
	v_med3_f32 v93, v93, s3, v10
	v_med3_f32 v94, v94, s3, v10
	v_med3_f32 v95, v95, s3, v10
	v_mov_b32_e32 v144, 0
	v_mov_b32_e32 v145, 0
	v_mov_b32_e32 v146, 0
	v_mov_b32_e32 v147, 0
	v_cvt_pk_fp8_f32 v144, v80, v81
	v_cvt_pk_fp8_f32 v145, v84, v85
	v_cvt_pk_fp8_f32 v146, v88, v89
	v_cvt_pk_fp8_f32 v147, v92, v93
	v_cvt_pk_fp8_f32 v144, v82, v83 op_sel:[0,0,1]
	v_cvt_pk_fp8_f32 v145, v86, v87 op_sel:[0,0,1]
	v_cvt_pk_fp8_f32 v146, v90, v91 op_sel:[0,0,1]
	v_cvt_pk_fp8_f32 v147, v94, v95 op_sel:[0,0,1]
	s_nop 0
	global_store_dwordx4 v[4:5], v[144:147], off
	v_lshl_add_u64 v[4:5], v[4:5], 0, s[14:15]
	global_load_dwordx4 v[80:83], v[6:7], off
	global_load_dwordx4 v[84:87], v[6:7], off offset:16
	global_load_dwordx4 v[88:91], v[6:7], off offset:32
	global_load_dwordx4 v[92:95], v[6:7], off offset:48
	v_lshl_add_u64 v[6:7], v[6:7], 0, s[6:7]
	s_waitcnt vmcnt(13)
	v_pk_mul_f32 v[96:97], v[96:97], s[20:21] op_sel_hi:[1,0]
	v_pk_mul_f32 v[98:99], v[98:99], s[20:21] op_sel_hi:[1,0]
	v_pk_mul_f32 v[100:101], v[100:101], s[20:21] op_sel_hi:[1,0]
	v_pk_mul_f32 v[102:103], v[102:103], s[20:21] op_sel_hi:[1,0]
	v_pk_mul_f32 v[104:105], v[104:105], s[20:21] op_sel_hi:[1,0]
	v_pk_mul_f32 v[106:107], v[106:107], s[20:21] op_sel_hi:[1,0]
	v_pk_mul_f32 v[108:109], v[108:109], s[20:21] op_sel_hi:[1,0]
	v_pk_mul_f32 v[110:111], v[110:111], s[20:21] op_sel_hi:[1,0]
	v_med3_f32 v96, v96, s3, v10
	v_med3_f32 v97, v97, s3, v10
	v_med3_f32 v98, v98, s3, v10
	v_med3_f32 v99, v99, s3, v10
	v_med3_f32 v100, v100, s3, v10
	v_med3_f32 v101, v101, s3, v10
	v_med3_f32 v102, v102, s3, v10
	v_med3_f32 v103, v103, s3, v10
	v_med3_f32 v104, v104, s3, v10
	v_med3_f32 v105, v105, s3, v10
	v_med3_f32 v106, v106, s3, v10
	v_med3_f32 v107, v107, s3, v10
	v_med3_f32 v108, v108, s3, v10
	v_med3_f32 v109, v109, s3, v10
	v_med3_f32 v110, v110, s3, v10
	v_med3_f32 v111, v111, s3, v10
	v_mov_b32_e32 v148, 0
	v_mov_b32_e32 v149, 0
	v_mov_b32_e32 v150, 0
	v_mov_b32_e32 v151, 0
	v_cvt_pk_fp8_f32 v148, v96, v97
	v_cvt_pk_fp8_f32 v149, v100, v101
	v_cvt_pk_fp8_f32 v150, v104, v105
	v_cvt_pk_fp8_f32 v151, v108, v109
	v_cvt_pk_fp8_f32 v148, v98, v99 op_sel:[0,0,1]
	v_cvt_pk_fp8_f32 v149, v102, v103 op_sel:[0,0,1]
	v_cvt_pk_fp8_f32 v150, v106, v107 op_sel:[0,0,1]
	v_cvt_pk_fp8_f32 v151, v110, v111 op_sel:[0,0,1]
	s_nop 0
	global_store_dwordx4 v[4:5], v[148:151], off
	v_lshl_add_u64 v[4:5], v[4:5], 0, s[14:15]
	global_load_dwordx4 v[96:99], v[6:7], off
	global_load_dwordx4 v[100:103], v[6:7], off offset:16
	global_load_dwordx4 v[104:107], v[6:7], off offset:32
	global_load_dwordx4 v[108:111], v[6:7], off offset:48
	v_lshl_add_u64 v[6:7], v[6:7], 0, s[6:7]
	s_waitcnt vmcnt(14)
	v_pk_mul_f32 v[112:113], v[112:113], s[20:21] op_sel_hi:[1,0]
	v_pk_mul_f32 v[114:115], v[114:115], s[20:21] op_sel_hi:[1,0]
	v_pk_mul_f32 v[116:117], v[116:117], s[20:21] op_sel_hi:[1,0]
	v_pk_mul_f32 v[118:119], v[118:119], s[20:21] op_sel_hi:[1,0]
	v_pk_mul_f32 v[120:121], v[120:121], s[20:21] op_sel_hi:[1,0]
	v_pk_mul_f32 v[122:123], v[122:123], s[20:21] op_sel_hi:[1,0]
	v_pk_mul_f32 v[124:125], v[124:125], s[20:21] op_sel_hi:[1,0]
	v_pk_mul_f32 v[126:127], v[126:127], s[20:21] op_sel_hi:[1,0]
	v_med3_f32 v112, v112, s3, v10
	v_med3_f32 v113, v113, s3, v10
	v_med3_f32 v114, v114, s3, v10
	v_med3_f32 v115, v115, s3, v10
	v_med3_f32 v116, v116, s3, v10
	v_med3_f32 v117, v117, s3, v10
	v_med3_f32 v118, v118, s3, v10
	v_med3_f32 v119, v119, s3, v10
	v_med3_f32 v120, v120, s3, v10
	v_med3_f32 v121, v121, s3, v10
	v_med3_f32 v122, v122, s3, v10
	v_med3_f32 v123, v123, s3, v10
	v_med3_f32 v124, v124, s3, v10
	v_med3_f32 v125, v125, s3, v10
	v_med3_f32 v126, v126, s3, v10
	v_med3_f32 v127, v127, s3, v10
	v_mov_b32_e32 v152, 0
	v_mov_b32_e32 v153, 0
	v_mov_b32_e32 v154, 0
	v_mov_b32_e32 v155, 0
	v_cvt_pk_fp8_f32 v152, v112, v113
	v_cvt_pk_fp8_f32 v153, v116, v117
	v_cvt_pk_fp8_f32 v154, v120, v121
	v_cvt_pk_fp8_f32 v155, v124, v125
	v_cvt_pk_fp8_f32 v152, v114, v115 op_sel:[0,0,1]
	v_cvt_pk_fp8_f32 v153, v118, v119 op_sel:[0,0,1]
	v_cvt_pk_fp8_f32 v154, v122, v123 op_sel:[0,0,1]
	v_cvt_pk_fp8_f32 v155, v126, v127 op_sel:[0,0,1]
	s_nop 0
	global_store_dwordx4 v[4:5], v[152:155], off
	v_lshl_add_u64 v[4:5], v[4:5], 0, s[14:15]
	global_load_dwordx4 v[112:115], v[6:7], off
	global_load_dwordx4 v[116:119], v[6:7], off offset:16
	global_load_dwordx4 v[120:123], v[6:7], off offset:32
	global_load_dwordx4 v[124:127], v[6:7], off offset:48
	v_lshl_add_u64 v[6:7], v[6:7], 0, s[6:7]
	s_waitcnt vmcnt(15)
	v_pk_mul_f32 v[128:129], v[128:129], s[20:21] op_sel_hi:[1,0]
	v_pk_mul_f32 v[130:131], v[130:131], s[20:21] op_sel_hi:[1,0]
	v_pk_mul_f32 v[132:133], v[132:133], s[20:21] op_sel_hi:[1,0]
	v_pk_mul_f32 v[134:135], v[134:135], s[20:21] op_sel_hi:[1,0]
	v_pk_mul_f32 v[136:137], v[136:137], s[20:21] op_sel_hi:[1,0]
	v_pk_mul_f32 v[138:139], v[138:139], s[20:21] op_sel_hi:[1,0]
	v_pk_mul_f32 v[140:141], v[140:141], s[20:21] op_sel_hi:[1,0]
	v_pk_mul_f32 v[142:143], v[142:143], s[20:21] op_sel_hi:[1,0]
	v_med3_f32 v128, v128, s3, v10
	v_med3_f32 v129, v129, s3, v10
	v_med3_f32 v130, v130, s3, v10
	v_med3_f32 v131, v131, s3, v10
	v_med3_f32 v132, v132, s3, v10
	v_med3_f32 v133, v133, s3, v10
	v_med3_f32 v134, v134, s3, v10
	v_med3_f32 v135, v135, s3, v10
	v_med3_f32 v136, v136, s3, v10
	v_med3_f32 v137, v137, s3, v10
	v_med3_f32 v138, v138, s3, v10
	v_med3_f32 v139, v139, s3, v10
	v_med3_f32 v140, v140, s3, v10
	v_med3_f32 v141, v141, s3, v10
	v_med3_f32 v142, v142, s3, v10
	v_med3_f32 v143, v143, s3, v10
	v_mov_b32_e32 v156, 0
	v_mov_b32_e32 v157, 0
	v_mov_b32_e32 v158, 0
	v_mov_b32_e32 v159, 0
	v_cvt_pk_fp8_f32 v156, v128, v129
	v_cvt_pk_fp8_f32 v157, v132, v133
	v_cvt_pk_fp8_f32 v158, v136, v137
	v_cvt_pk_fp8_f32 v159, v140, v141
	v_cvt_pk_fp8_f32 v156, v130, v131 op_sel:[0,0,1]
	v_cvt_pk_fp8_f32 v157, v134, v135 op_sel:[0,0,1]
	v_cvt_pk_fp8_f32 v158, v138, v139 op_sel:[0,0,1]
	v_cvt_pk_fp8_f32 v159, v142, v143 op_sel:[0,0,1]
	s_nop 0
	global_store_dwordx4 v[4:5], v[156:159], off
	v_lshl_add_u64 v[4:5], v[4:5], 0, s[14:15]
	global_load_dwordx4 v[128:131], v[6:7], off
	global_load_dwordx4 v[132:135], v[6:7], off offset:16
	global_load_dwordx4 v[136:139], v[6:7], off offset:32
	global_load_dwordx4 v[140:143], v[6:7], off offset:48
	v_lshl_add_u64 v[6:7], v[6:7], 0, s[6:7]
	s_waitcnt vmcnt(15)
	v_pk_mul_f32 v[80:81], v[80:81], s[20:21] op_sel_hi:[1,0]
	v_pk_mul_f32 v[82:83], v[82:83], s[20:21] op_sel_hi:[1,0]
	v_pk_mul_f32 v[84:85], v[84:85], s[20:21] op_sel_hi:[1,0]
	v_pk_mul_f32 v[86:87], v[86:87], s[20:21] op_sel_hi:[1,0]
	v_pk_mul_f32 v[88:89], v[88:89], s[20:21] op_sel_hi:[1,0]
	v_pk_mul_f32 v[90:91], v[90:91], s[20:21] op_sel_hi:[1,0]
	v_pk_mul_f32 v[92:93], v[92:93], s[20:21] op_sel_hi:[1,0]
	v_pk_mul_f32 v[94:95], v[94:95], s[20:21] op_sel_hi:[1,0]
	v_med3_f32 v80, v80, s3, v10
	v_med3_f32 v81, v81, s3, v10
	v_med3_f32 v82, v82, s3, v10
	v_med3_f32 v83, v83, s3, v10
	v_med3_f32 v84, v84, s3, v10
	v_med3_f32 v85, v85, s3, v10
	v_med3_f32 v86, v86, s3, v10
	v_med3_f32 v87, v87, s3, v10
	v_med3_f32 v88, v88, s3, v10
	v_med3_f32 v89, v89, s3, v10
	v_med3_f32 v90, v90, s3, v10
	v_med3_f32 v91, v91, s3, v10
	v_med3_f32 v92, v92, s3, v10
	v_med3_f32 v93, v93, s3, v10
	v_med3_f32 v94, v94, s3, v10
	v_med3_f32 v95, v95, s3, v10
	v_mov_b32_e32 v144, 0
	v_mov_b32_e32 v145, 0
	v_mov_b32_e32 v146, 0
	v_mov_b32_e32 v147, 0
	v_cvt_pk_fp8_f32 v144, v80, v81
	v_cvt_pk_fp8_f32 v145, v84, v85
	v_cvt_pk_fp8_f32 v146, v88, v89
	v_cvt_pk_fp8_f32 v147, v92, v93
	v_cvt_pk_fp8_f32 v144, v82, v83 op_sel:[0,0,1]
	v_cvt_pk_fp8_f32 v145, v86, v87 op_sel:[0,0,1]
	v_cvt_pk_fp8_f32 v146, v90, v91 op_sel:[0,0,1]
	v_cvt_pk_fp8_f32 v147, v94, v95 op_sel:[0,0,1]
	s_nop 0
	global_store_dwordx4 v[4:5], v[144:147], off
	v_lshl_add_u64 v[4:5], v[4:5], 0, s[14:15]
	global_load_dwordx4 v[80:83], v[6:7], off
	global_load_dwordx4 v[84:87], v[6:7], off offset:16
	global_load_dwordx4 v[88:91], v[6:7], off offset:32
	global_load_dwordx4 v[92:95], v[6:7], off offset:48
	v_lshl_add_u64 v[6:7], v[6:7], 0, s[6:7]
	s_waitcnt vmcnt(15)
	v_pk_mul_f32 v[96:97], v[96:97], s[20:21] op_sel_hi:[1,0]
	v_pk_mul_f32 v[98:99], v[98:99], s[20:21] op_sel_hi:[1,0]
	v_pk_mul_f32 v[100:101], v[100:101], s[20:21] op_sel_hi:[1,0]
	v_pk_mul_f32 v[102:103], v[102:103], s[20:21] op_sel_hi:[1,0]
	v_pk_mul_f32 v[104:105], v[104:105], s[20:21] op_sel_hi:[1,0]
	v_pk_mul_f32 v[106:107], v[106:107], s[20:21] op_sel_hi:[1,0]
	v_pk_mul_f32 v[108:109], v[108:109], s[20:21] op_sel_hi:[1,0]
	v_pk_mul_f32 v[110:111], v[110:111], s[20:21] op_sel_hi:[1,0]
	v_med3_f32 v96, v96, s3, v10
	v_med3_f32 v97, v97, s3, v10
	v_med3_f32 v98, v98, s3, v10
	v_med3_f32 v99, v99, s3, v10
	v_med3_f32 v100, v100, s3, v10
	v_med3_f32 v101, v101, s3, v10
	v_med3_f32 v102, v102, s3, v10
	v_med3_f32 v103, v103, s3, v10
	v_med3_f32 v104, v104, s3, v10
	v_med3_f32 v105, v105, s3, v10
	v_med3_f32 v106, v106, s3, v10
	v_med3_f32 v107, v107, s3, v10
	v_med3_f32 v108, v108, s3, v10
	v_med3_f32 v109, v109, s3, v10
	v_med3_f32 v110, v110, s3, v10
	v_med3_f32 v111, v111, s3, v10
	v_mov_b32_e32 v148, 0
	v_mov_b32_e32 v149, 0
	v_mov_b32_e32 v150, 0
	v_mov_b32_e32 v151, 0
	v_cvt_pk_fp8_f32 v148, v96, v97
	v_cvt_pk_fp8_f32 v149, v100, v101
	v_cvt_pk_fp8_f32 v150, v104, v105
	v_cvt_pk_fp8_f32 v151, v108, v109
	v_cvt_pk_fp8_f32 v148, v98, v99 op_sel:[0,0,1]
	v_cvt_pk_fp8_f32 v149, v102, v103 op_sel:[0,0,1]
	v_cvt_pk_fp8_f32 v150, v106, v107 op_sel:[0,0,1]
	v_cvt_pk_fp8_f32 v151, v110, v111 op_sel:[0,0,1]
	s_nop 0
	global_store_dwordx4 v[4:5], v[148:151], off
	v_lshl_add_u64 v[4:5], v[4:5], 0, s[14:15]
	global_load_dwordx4 v[96:99], v[6:7], off
	global_load_dwordx4 v[100:103], v[6:7], off offset:16
	global_load_dwordx4 v[104:107], v[6:7], off offset:32
	global_load_dwordx4 v[108:111], v[6:7], off offset:48
	v_lshl_add_u64 v[6:7], v[6:7], 0, s[6:7]
	s_waitcnt vmcnt(15)
	v_pk_mul_f32 v[112:113], v[112:113], s[20:21] op_sel_hi:[1,0]
	v_pk_mul_f32 v[114:115], v[114:115], s[20:21] op_sel_hi:[1,0]
	v_pk_mul_f32 v[116:117], v[116:117], s[20:21] op_sel_hi:[1,0]
	v_pk_mul_f32 v[118:119], v[118:119], s[20:21] op_sel_hi:[1,0]
	v_pk_mul_f32 v[120:121], v[120:121], s[20:21] op_sel_hi:[1,0]
	v_pk_mul_f32 v[122:123], v[122:123], s[20:21] op_sel_hi:[1,0]
	v_pk_mul_f32 v[124:125], v[124:125], s[20:21] op_sel_hi:[1,0]
	v_pk_mul_f32 v[126:127], v[126:127], s[20:21] op_sel_hi:[1,0]
	v_med3_f32 v112, v112, s3, v10
	v_med3_f32 v113, v113, s3, v10
	v_med3_f32 v114, v114, s3, v10
	v_med3_f32 v115, v115, s3, v10
	v_med3_f32 v116, v116, s3, v10
	v_med3_f32 v117, v117, s3, v10
	v_med3_f32 v118, v118, s3, v10
	v_med3_f32 v119, v119, s3, v10
	v_med3_f32 v120, v120, s3, v10
	v_med3_f32 v121, v121, s3, v10
	v_med3_f32 v122, v122, s3, v10
	v_med3_f32 v123, v123, s3, v10
	v_med3_f32 v124, v124, s3, v10
	v_med3_f32 v125, v125, s3, v10
	v_med3_f32 v126, v126, s3, v10
	v_med3_f32 v127, v127, s3, v10
	v_mov_b32_e32 v152, 0
	v_mov_b32_e32 v153, 0
	v_mov_b32_e32 v154, 0
	v_mov_b32_e32 v155, 0
	v_cvt_pk_fp8_f32 v152, v112, v113
	v_cvt_pk_fp8_f32 v153, v116, v117
	v_cvt_pk_fp8_f32 v154, v120, v121
	v_cvt_pk_fp8_f32 v155, v124, v125
	v_cvt_pk_fp8_f32 v152, v114, v115 op_sel:[0,0,1]
	v_cvt_pk_fp8_f32 v153, v118, v119 op_sel:[0,0,1]
	v_cvt_pk_fp8_f32 v154, v122, v123 op_sel:[0,0,1]
	v_cvt_pk_fp8_f32 v155, v126, v127 op_sel:[0,0,1]
	s_nop 0
	global_store_dwordx4 v[4:5], v[152:155], off
	v_lshl_add_u64 v[4:5], v[4:5], 0, s[14:15]
	global_load_dwordx4 v[112:115], v[6:7], off
	global_load_dwordx4 v[116:119], v[6:7], off offset:16
	global_load_dwordx4 v[120:123], v[6:7], off offset:32
	global_load_dwordx4 v[124:127], v[6:7], off offset:48
	v_lshl_add_u64 v[6:7], v[6:7], 0, s[6:7]
	s_waitcnt vmcnt(15)
	v_pk_mul_f32 v[128:129], v[128:129], s[20:21] op_sel_hi:[1,0]
	v_pk_mul_f32 v[130:131], v[130:131], s[20:21] op_sel_hi:[1,0]
	v_pk_mul_f32 v[132:133], v[132:133], s[20:21] op_sel_hi:[1,0]
	v_pk_mul_f32 v[134:135], v[134:135], s[20:21] op_sel_hi:[1,0]
	v_pk_mul_f32 v[136:137], v[136:137], s[20:21] op_sel_hi:[1,0]
	v_pk_mul_f32 v[138:139], v[138:139], s[20:21] op_sel_hi:[1,0]
	v_pk_mul_f32 v[140:141], v[140:141], s[20:21] op_sel_hi:[1,0]
	v_pk_mul_f32 v[142:143], v[142:143], s[20:21] op_sel_hi:[1,0]
	v_med3_f32 v128, v128, s3, v10
	v_med3_f32 v129, v129, s3, v10
	v_med3_f32 v130, v130, s3, v10
	v_med3_f32 v131, v131, s3, v10
	v_med3_f32 v132, v132, s3, v10
	v_med3_f32 v133, v133, s3, v10
	v_med3_f32 v134, v134, s3, v10
	v_med3_f32 v135, v135, s3, v10
	v_med3_f32 v136, v136, s3, v10
	v_med3_f32 v137, v137, s3, v10
	v_med3_f32 v138, v138, s3, v10
	v_med3_f32 v139, v139, s3, v10
	v_med3_f32 v140, v140, s3, v10
	v_med3_f32 v141, v141, s3, v10
	v_med3_f32 v142, v142, s3, v10
	v_med3_f32 v143, v143, s3, v10
	v_mov_b32_e32 v156, 0
	v_mov_b32_e32 v157, 0
	v_mov_b32_e32 v158, 0
	v_mov_b32_e32 v159, 0
	v_cvt_pk_fp8_f32 v156, v128, v129
	v_cvt_pk_fp8_f32 v157, v132, v133
	v_cvt_pk_fp8_f32 v158, v136, v137
	v_cvt_pk_fp8_f32 v159, v140, v141
	v_cvt_pk_fp8_f32 v156, v130, v131 op_sel:[0,0,1]
	v_cvt_pk_fp8_f32 v157, v134, v135 op_sel:[0,0,1]
	v_cvt_pk_fp8_f32 v158, v138, v139 op_sel:[0,0,1]
	v_cvt_pk_fp8_f32 v159, v142, v143 op_sel:[0,0,1]
	s_nop 0
	global_store_dwordx4 v[4:5], v[156:159], off
	v_lshl_add_u64 v[4:5], v[4:5], 0, s[14:15]
	global_load_dwordx4 v[128:131], v[6:7], off
	global_load_dwordx4 v[132:135], v[6:7], off offset:16
	global_load_dwordx4 v[136:139], v[6:7], off offset:32
	global_load_dwordx4 v[140:143], v[6:7], off offset:48
	v_lshl_add_u64 v[6:7], v[6:7], 0, s[6:7]
	s_waitcnt vmcnt(15)
	v_pk_mul_f32 v[80:81], v[80:81], s[20:21] op_sel_hi:[1,0]
	v_pk_mul_f32 v[82:83], v[82:83], s[20:21] op_sel_hi:[1,0]
	v_pk_mul_f32 v[84:85], v[84:85], s[20:21] op_sel_hi:[1,0]
	v_pk_mul_f32 v[86:87], v[86:87], s[20:21] op_sel_hi:[1,0]
	v_pk_mul_f32 v[88:89], v[88:89], s[20:21] op_sel_hi:[1,0]
	v_pk_mul_f32 v[90:91], v[90:91], s[20:21] op_sel_hi:[1,0]
	v_pk_mul_f32 v[92:93], v[92:93], s[20:21] op_sel_hi:[1,0]
	v_pk_mul_f32 v[94:95], v[94:95], s[20:21] op_sel_hi:[1,0]
	v_med3_f32 v80, v80, s3, v10
	v_med3_f32 v81, v81, s3, v10
	v_med3_f32 v82, v82, s3, v10
	v_med3_f32 v83, v83, s3, v10
	v_med3_f32 v84, v84, s3, v10
	v_med3_f32 v85, v85, s3, v10
	v_med3_f32 v86, v86, s3, v10
	v_med3_f32 v87, v87, s3, v10
	v_med3_f32 v88, v88, s3, v10
	v_med3_f32 v89, v89, s3, v10
	v_med3_f32 v90, v90, s3, v10
	v_med3_f32 v91, v91, s3, v10
	v_med3_f32 v92, v92, s3, v10
	v_med3_f32 v93, v93, s3, v10
	v_med3_f32 v94, v94, s3, v10
	v_med3_f32 v95, v95, s3, v10
	v_mov_b32_e32 v144, 0
	v_mov_b32_e32 v145, 0
	v_mov_b32_e32 v146, 0
	v_mov_b32_e32 v147, 0
	v_cvt_pk_fp8_f32 v144, v80, v81
	v_cvt_pk_fp8_f32 v145, v84, v85
	v_cvt_pk_fp8_f32 v146, v88, v89
	v_cvt_pk_fp8_f32 v147, v92, v93
	v_cvt_pk_fp8_f32 v144, v82, v83 op_sel:[0,0,1]
	v_cvt_pk_fp8_f32 v145, v86, v87 op_sel:[0,0,1]
	v_cvt_pk_fp8_f32 v146, v90, v91 op_sel:[0,0,1]
	v_cvt_pk_fp8_f32 v147, v94, v95 op_sel:[0,0,1]
	s_nop 0
	global_store_dwordx4 v[4:5], v[144:147], off
	v_lshl_add_u64 v[4:5], v[4:5], 0, s[14:15]
	global_load_dwordx4 v[80:83], v[6:7], off
	global_load_dwordx4 v[84:87], v[6:7], off offset:16
	global_load_dwordx4 v[88:91], v[6:7], off offset:32
	global_load_dwordx4 v[92:95], v[6:7], off offset:48
	v_lshl_add_u64 v[6:7], v[6:7], 0, s[6:7]
	s_waitcnt vmcnt(15)
	v_pk_mul_f32 v[96:97], v[96:97], s[20:21] op_sel_hi:[1,0]
	v_pk_mul_f32 v[98:99], v[98:99], s[20:21] op_sel_hi:[1,0]
	v_pk_mul_f32 v[100:101], v[100:101], s[20:21] op_sel_hi:[1,0]
	v_pk_mul_f32 v[102:103], v[102:103], s[20:21] op_sel_hi:[1,0]
	v_pk_mul_f32 v[104:105], v[104:105], s[20:21] op_sel_hi:[1,0]
	v_pk_mul_f32 v[106:107], v[106:107], s[20:21] op_sel_hi:[1,0]
	v_pk_mul_f32 v[108:109], v[108:109], s[20:21] op_sel_hi:[1,0]
	v_pk_mul_f32 v[110:111], v[110:111], s[20:21] op_sel_hi:[1,0]
	v_med3_f32 v96, v96, s3, v10
	v_med3_f32 v97, v97, s3, v10
	v_med3_f32 v98, v98, s3, v10
	v_med3_f32 v99, v99, s3, v10
	v_med3_f32 v100, v100, s3, v10
	v_med3_f32 v101, v101, s3, v10
	v_med3_f32 v102, v102, s3, v10
	v_med3_f32 v103, v103, s3, v10
	v_med3_f32 v104, v104, s3, v10
	v_med3_f32 v105, v105, s3, v10
	v_med3_f32 v106, v106, s3, v10
	v_med3_f32 v107, v107, s3, v10
	v_med3_f32 v108, v108, s3, v10
	v_med3_f32 v109, v109, s3, v10
	v_med3_f32 v110, v110, s3, v10
	v_med3_f32 v111, v111, s3, v10
	v_mov_b32_e32 v148, 0
	v_mov_b32_e32 v149, 0
	v_mov_b32_e32 v150, 0
	v_mov_b32_e32 v151, 0
	v_cvt_pk_fp8_f32 v148, v96, v97
	v_cvt_pk_fp8_f32 v149, v100, v101
	v_cvt_pk_fp8_f32 v150, v104, v105
	v_cvt_pk_fp8_f32 v151, v108, v109
	v_cvt_pk_fp8_f32 v148, v98, v99 op_sel:[0,0,1]
	v_cvt_pk_fp8_f32 v149, v102, v103 op_sel:[0,0,1]
	v_cvt_pk_fp8_f32 v150, v106, v107 op_sel:[0,0,1]
	v_cvt_pk_fp8_f32 v151, v110, v111 op_sel:[0,0,1]
	s_nop 0
	global_store_dwordx4 v[4:5], v[148:151], off
	v_lshl_add_u64 v[4:5], v[4:5], 0, s[14:15]
	global_load_dwordx4 v[96:99], v[6:7], off
	global_load_dwordx4 v[100:103], v[6:7], off offset:16
	global_load_dwordx4 v[104:107], v[6:7], off offset:32
	global_load_dwordx4 v[108:111], v[6:7], off offset:48
	v_lshl_add_u64 v[6:7], v[6:7], 0, s[6:7]
	s_waitcnt vmcnt(15)
	v_pk_mul_f32 v[112:113], v[112:113], s[20:21] op_sel_hi:[1,0]
	v_pk_mul_f32 v[114:115], v[114:115], s[20:21] op_sel_hi:[1,0]
	v_pk_mul_f32 v[116:117], v[116:117], s[20:21] op_sel_hi:[1,0]
	v_pk_mul_f32 v[118:119], v[118:119], s[20:21] op_sel_hi:[1,0]
	v_pk_mul_f32 v[120:121], v[120:121], s[20:21] op_sel_hi:[1,0]
	v_pk_mul_f32 v[122:123], v[122:123], s[20:21] op_sel_hi:[1,0]
	v_pk_mul_f32 v[124:125], v[124:125], s[20:21] op_sel_hi:[1,0]
	v_pk_mul_f32 v[126:127], v[126:127], s[20:21] op_sel_hi:[1,0]
	v_med3_f32 v112, v112, s3, v10
	v_med3_f32 v113, v113, s3, v10
	v_med3_f32 v114, v114, s3, v10
	v_med3_f32 v115, v115, s3, v10
	v_med3_f32 v116, v116, s3, v10
	v_med3_f32 v117, v117, s3, v10
	v_med3_f32 v118, v118, s3, v10
	v_med3_f32 v119, v119, s3, v10
	v_med3_f32 v120, v120, s3, v10
	v_med3_f32 v121, v121, s3, v10
	v_med3_f32 v122, v122, s3, v10
	v_med3_f32 v123, v123, s3, v10
	v_med3_f32 v124, v124, s3, v10
	v_med3_f32 v125, v125, s3, v10
	v_med3_f32 v126, v126, s3, v10
	v_med3_f32 v127, v127, s3, v10
	v_mov_b32_e32 v152, 0
	v_mov_b32_e32 v153, 0
	v_mov_b32_e32 v154, 0
	v_mov_b32_e32 v155, 0
	v_cvt_pk_fp8_f32 v152, v112, v113
	v_cvt_pk_fp8_f32 v153, v116, v117
	v_cvt_pk_fp8_f32 v154, v120, v121
	v_cvt_pk_fp8_f32 v155, v124, v125
	v_cvt_pk_fp8_f32 v152, v114, v115 op_sel:[0,0,1]
	v_cvt_pk_fp8_f32 v153, v118, v119 op_sel:[0,0,1]
	v_cvt_pk_fp8_f32 v154, v122, v123 op_sel:[0,0,1]
	v_cvt_pk_fp8_f32 v155, v126, v127 op_sel:[0,0,1]
	s_nop 0
	global_store_dwordx4 v[4:5], v[152:155], off
	v_lshl_add_u64 v[4:5], v[4:5], 0, s[14:15]
	global_load_dwordx4 v[112:115], v[6:7], off
	global_load_dwordx4 v[116:119], v[6:7], off offset:16
	global_load_dwordx4 v[120:123], v[6:7], off offset:32
	global_load_dwordx4 v[124:127], v[6:7], off offset:48
	v_lshl_add_u64 v[6:7], v[6:7], 0, s[6:7]
	s_waitcnt vmcnt(15)
	v_pk_mul_f32 v[128:129], v[128:129], s[20:21] op_sel_hi:[1,0]
	v_pk_mul_f32 v[130:131], v[130:131], s[20:21] op_sel_hi:[1,0]
	v_pk_mul_f32 v[132:133], v[132:133], s[20:21] op_sel_hi:[1,0]
	v_pk_mul_f32 v[134:135], v[134:135], s[20:21] op_sel_hi:[1,0]
	v_pk_mul_f32 v[136:137], v[136:137], s[20:21] op_sel_hi:[1,0]
	v_pk_mul_f32 v[138:139], v[138:139], s[20:21] op_sel_hi:[1,0]
	v_pk_mul_f32 v[140:141], v[140:141], s[20:21] op_sel_hi:[1,0]
	v_pk_mul_f32 v[142:143], v[142:143], s[20:21] op_sel_hi:[1,0]
	v_med3_f32 v128, v128, s3, v10
	v_med3_f32 v129, v129, s3, v10
	v_med3_f32 v130, v130, s3, v10
	v_med3_f32 v131, v131, s3, v10
	v_med3_f32 v132, v132, s3, v10
	v_med3_f32 v133, v133, s3, v10
	v_med3_f32 v134, v134, s3, v10
	v_med3_f32 v135, v135, s3, v10
	v_med3_f32 v136, v136, s3, v10
	v_med3_f32 v137, v137, s3, v10
	v_med3_f32 v138, v138, s3, v10
	v_med3_f32 v139, v139, s3, v10
	v_med3_f32 v140, v140, s3, v10
	v_med3_f32 v141, v141, s3, v10
	v_med3_f32 v142, v142, s3, v10
	v_med3_f32 v143, v143, s3, v10
	v_mov_b32_e32 v156, 0
	v_mov_b32_e32 v157, 0
	v_mov_b32_e32 v158, 0
	v_mov_b32_e32 v159, 0
	v_cvt_pk_fp8_f32 v156, v128, v129
	v_cvt_pk_fp8_f32 v157, v132, v133
	v_cvt_pk_fp8_f32 v158, v136, v137
	v_cvt_pk_fp8_f32 v159, v140, v141
	v_cvt_pk_fp8_f32 v156, v130, v131 op_sel:[0,0,1]
	v_cvt_pk_fp8_f32 v157, v134, v135 op_sel:[0,0,1]
	v_cvt_pk_fp8_f32 v158, v138, v139 op_sel:[0,0,1]
	v_cvt_pk_fp8_f32 v159, v142, v143 op_sel:[0,0,1]
	s_nop 0
	global_store_dwordx4 v[4:5], v[156:159], off
	v_lshl_add_u64 v[4:5], v[4:5], 0, s[14:15]
	global_load_dwordx4 v[128:131], v[6:7], off
	global_load_dwordx4 v[132:135], v[6:7], off offset:16
	global_load_dwordx4 v[136:139], v[6:7], off offset:32
	global_load_dwordx4 v[140:143], v[6:7], off offset:48
	v_lshl_add_u64 v[6:7], v[6:7], 0, s[6:7]
	s_waitcnt vmcnt(15)
	v_pk_mul_f32 v[80:81], v[80:81], s[20:21] op_sel_hi:[1,0]
	v_pk_mul_f32 v[82:83], v[82:83], s[20:21] op_sel_hi:[1,0]
	v_pk_mul_f32 v[84:85], v[84:85], s[20:21] op_sel_hi:[1,0]
	v_pk_mul_f32 v[86:87], v[86:87], s[20:21] op_sel_hi:[1,0]
	v_pk_mul_f32 v[88:89], v[88:89], s[20:21] op_sel_hi:[1,0]
	v_pk_mul_f32 v[90:91], v[90:91], s[20:21] op_sel_hi:[1,0]
	v_pk_mul_f32 v[92:93], v[92:93], s[20:21] op_sel_hi:[1,0]
	v_pk_mul_f32 v[94:95], v[94:95], s[20:21] op_sel_hi:[1,0]
	v_med3_f32 v80, v80, s3, v10
	v_med3_f32 v81, v81, s3, v10
	v_med3_f32 v82, v82, s3, v10
	v_med3_f32 v83, v83, s3, v10
	v_med3_f32 v84, v84, s3, v10
	v_med3_f32 v85, v85, s3, v10
	v_med3_f32 v86, v86, s3, v10
	v_med3_f32 v87, v87, s3, v10
	v_med3_f32 v88, v88, s3, v10
	v_med3_f32 v89, v89, s3, v10
	v_med3_f32 v90, v90, s3, v10
	v_med3_f32 v91, v91, s3, v10
	v_med3_f32 v92, v92, s3, v10
	v_med3_f32 v93, v93, s3, v10
	v_med3_f32 v94, v94, s3, v10
	v_med3_f32 v95, v95, s3, v10
	v_mov_b32_e32 v144, 0
	v_mov_b32_e32 v145, 0
	v_mov_b32_e32 v146, 0
	v_mov_b32_e32 v147, 0
	v_cvt_pk_fp8_f32 v144, v80, v81
	v_cvt_pk_fp8_f32 v145, v84, v85
	v_cvt_pk_fp8_f32 v146, v88, v89
	v_cvt_pk_fp8_f32 v147, v92, v93
	v_cvt_pk_fp8_f32 v144, v82, v83 op_sel:[0,0,1]
	v_cvt_pk_fp8_f32 v145, v86, v87 op_sel:[0,0,1]
	v_cvt_pk_fp8_f32 v146, v90, v91 op_sel:[0,0,1]
	v_cvt_pk_fp8_f32 v147, v94, v95 op_sel:[0,0,1]
	s_nop 0
	global_store_dwordx4 v[4:5], v[144:147], off
	v_lshl_add_u64 v[4:5], v[4:5], 0, s[14:15]
	s_waitcnt vmcnt(11)
	v_pk_mul_f32 v[96:97], v[96:97], s[20:21] op_sel_hi:[1,0]
	v_pk_mul_f32 v[98:99], v[98:99], s[20:21] op_sel_hi:[1,0]
	v_pk_mul_f32 v[100:101], v[100:101], s[20:21] op_sel_hi:[1,0]
	v_pk_mul_f32 v[102:103], v[102:103], s[20:21] op_sel_hi:[1,0]
	v_pk_mul_f32 v[104:105], v[104:105], s[20:21] op_sel_hi:[1,0]
	v_pk_mul_f32 v[106:107], v[106:107], s[20:21] op_sel_hi:[1,0]
	v_pk_mul_f32 v[108:109], v[108:109], s[20:21] op_sel_hi:[1,0]
	v_pk_mul_f32 v[110:111], v[110:111], s[20:21] op_sel_hi:[1,0]
	v_med3_f32 v96, v96, s3, v10
	v_med3_f32 v97, v97, s3, v10
	v_med3_f32 v98, v98, s3, v10
	v_med3_f32 v99, v99, s3, v10
	v_med3_f32 v100, v100, s3, v10
	v_med3_f32 v101, v101, s3, v10
	v_med3_f32 v102, v102, s3, v10
	v_med3_f32 v103, v103, s3, v10
	v_med3_f32 v104, v104, s3, v10
	v_med3_f32 v105, v105, s3, v10
	v_med3_f32 v106, v106, s3, v10
	v_med3_f32 v107, v107, s3, v10
	v_med3_f32 v108, v108, s3, v10
	v_med3_f32 v109, v109, s3, v10
	v_med3_f32 v110, v110, s3, v10
	v_med3_f32 v111, v111, s3, v10
	v_mov_b32_e32 v148, 0
	v_mov_b32_e32 v149, 0
	v_mov_b32_e32 v150, 0
	v_mov_b32_e32 v151, 0
	v_cvt_pk_fp8_f32 v148, v96, v97
	v_cvt_pk_fp8_f32 v149, v100, v101
	v_cvt_pk_fp8_f32 v150, v104, v105
	v_cvt_pk_fp8_f32 v151, v108, v109
	v_cvt_pk_fp8_f32 v148, v98, v99 op_sel:[0,0,1]
	v_cvt_pk_fp8_f32 v149, v102, v103 op_sel:[0,0,1]
	v_cvt_pk_fp8_f32 v150, v106, v107 op_sel:[0,0,1]
	v_cvt_pk_fp8_f32 v151, v110, v111 op_sel:[0,0,1]
	s_nop 0
	global_store_dwordx4 v[4:5], v[148:151], off
	v_lshl_add_u64 v[4:5], v[4:5], 0, s[14:15]
	s_waitcnt vmcnt(7)
	v_pk_mul_f32 v[112:113], v[112:113], s[20:21] op_sel_hi:[1,0]
	v_pk_mul_f32 v[114:115], v[114:115], s[20:21] op_sel_hi:[1,0]
	v_pk_mul_f32 v[116:117], v[116:117], s[20:21] op_sel_hi:[1,0]
	v_pk_mul_f32 v[118:119], v[118:119], s[20:21] op_sel_hi:[1,0]
	v_pk_mul_f32 v[120:121], v[120:121], s[20:21] op_sel_hi:[1,0]
	v_pk_mul_f32 v[122:123], v[122:123], s[20:21] op_sel_hi:[1,0]
	v_pk_mul_f32 v[124:125], v[124:125], s[20:21] op_sel_hi:[1,0]
	v_pk_mul_f32 v[126:127], v[126:127], s[20:21] op_sel_hi:[1,0]
	v_med3_f32 v112, v112, s3, v10
	v_med3_f32 v113, v113, s3, v10
	v_med3_f32 v114, v114, s3, v10
	v_med3_f32 v115, v115, s3, v10
	v_med3_f32 v116, v116, s3, v10
	v_med3_f32 v117, v117, s3, v10
	v_med3_f32 v118, v118, s3, v10
	v_med3_f32 v119, v119, s3, v10
	v_med3_f32 v120, v120, s3, v10
	v_med3_f32 v121, v121, s3, v10
	v_med3_f32 v122, v122, s3, v10
	v_med3_f32 v123, v123, s3, v10
	v_med3_f32 v124, v124, s3, v10
	v_med3_f32 v125, v125, s3, v10
	v_med3_f32 v126, v126, s3, v10
	v_med3_f32 v127, v127, s3, v10
	v_mov_b32_e32 v152, 0
	v_mov_b32_e32 v153, 0
	v_mov_b32_e32 v154, 0
	v_mov_b32_e32 v155, 0
	v_cvt_pk_fp8_f32 v152, v112, v113
	v_cvt_pk_fp8_f32 v153, v116, v117
	v_cvt_pk_fp8_f32 v154, v120, v121
	v_cvt_pk_fp8_f32 v155, v124, v125
	v_cvt_pk_fp8_f32 v152, v114, v115 op_sel:[0,0,1]
	v_cvt_pk_fp8_f32 v153, v118, v119 op_sel:[0,0,1]
	v_cvt_pk_fp8_f32 v154, v122, v123 op_sel:[0,0,1]
	v_cvt_pk_fp8_f32 v155, v126, v127 op_sel:[0,0,1]
	s_nop 0
	global_store_dwordx4 v[4:5], v[152:155], off
	v_lshl_add_u64 v[4:5], v[4:5], 0, s[14:15]
	s_waitcnt vmcnt(3)
	v_pk_mul_f32 v[128:129], v[128:129], s[20:21] op_sel_hi:[1,0]
	v_pk_mul_f32 v[130:131], v[130:131], s[20:21] op_sel_hi:[1,0]
	v_pk_mul_f32 v[132:133], v[132:133], s[20:21] op_sel_hi:[1,0]
	v_pk_mul_f32 v[134:135], v[134:135], s[20:21] op_sel_hi:[1,0]
	v_pk_mul_f32 v[136:137], v[136:137], s[20:21] op_sel_hi:[1,0]
	v_pk_mul_f32 v[138:139], v[138:139], s[20:21] op_sel_hi:[1,0]
	v_pk_mul_f32 v[140:141], v[140:141], s[20:21] op_sel_hi:[1,0]
	v_pk_mul_f32 v[142:143], v[142:143], s[20:21] op_sel_hi:[1,0]
	v_med3_f32 v128, v128, s3, v10
	v_med3_f32 v129, v129, s3, v10
	v_med3_f32 v130, v130, s3, v10
	v_med3_f32 v131, v131, s3, v10
	v_med3_f32 v132, v132, s3, v10
	v_med3_f32 v133, v133, s3, v10
	v_med3_f32 v134, v134, s3, v10
	v_med3_f32 v135, v135, s3, v10
	v_med3_f32 v136, v136, s3, v10
	v_med3_f32 v137, v137, s3, v10
	v_med3_f32 v138, v138, s3, v10
	v_med3_f32 v139, v139, s3, v10
	v_med3_f32 v140, v140, s3, v10
	v_med3_f32 v141, v141, s3, v10
	v_med3_f32 v142, v142, s3, v10
	v_med3_f32 v143, v143, s3, v10
	v_mov_b32_e32 v156, 0
	v_mov_b32_e32 v157, 0
	v_mov_b32_e32 v158, 0
	v_mov_b32_e32 v159, 0
	v_cvt_pk_fp8_f32 v156, v128, v129
	v_cvt_pk_fp8_f32 v157, v132, v133
	v_cvt_pk_fp8_f32 v158, v136, v137
	v_cvt_pk_fp8_f32 v159, v140, v141
	v_cvt_pk_fp8_f32 v156, v130, v131 op_sel:[0,0,1]
	v_cvt_pk_fp8_f32 v157, v134, v135 op_sel:[0,0,1]
	v_cvt_pk_fp8_f32 v158, v138, v139 op_sel:[0,0,1]
	v_cvt_pk_fp8_f32 v159, v142, v143 op_sel:[0,0,1]
	s_nop 0
	global_store_dwordx4 v[4:5], v[156:159], off
	v_lshl_add_u64 v[4:5], v[4:5], 0, s[14:15]
	s_branch .LBB0_38
